# v36 + next-layer weight transposes moved from mixer queue to idle WGs of in-proj last round (LDS-free dwordx4 transpose)
# baseline (speedup 1.0000x reference)
.LBB0_8:
	s_cmp_eq_u32 s12, 2
	s_cselect_b32 s32, 1, 0
	s_cmp_eq_u32 s12, 9
	s_cselect_b32 s32, 2, s32
	s_cmp_eq_u32 s12, 16
	s_cselect_b32 s32, 3, s32
	s_cmp_eq_u32 s32, 0
	s_cbranch_scc1 .Lmy_tf_done
	v_readlane_b32 s41, v251, 0
	s_sub_i32 s41, s41, 0x50
	s_cmp_lt_i32 s41, 0
	s_cbranch_scc1 .Lmy_tf_done
	s_mov_b64 s[38:39], exec
	s_mov_b64 exec, -1
	s_waitcnt vmcnt(0) lgkmcnt(0)
	s_sub_u32 s98, s96, 0xd0
	s_subb_u32 s99, s97, 0
	s_load_dwordx2 s[60:61], s[98:99], 0x40
	s_load_dwordx2 s[62:63], s[98:99], 0x48
	s_load_dwordx2 s[64:65], s[98:99], 0xa0
	s_load_dwordx2 s[68:69], s[98:99], 0xa8
	v_readfirstlane_b32 s44, v155
	s_lshr_b32 s44, s44, 6
	v_and_b32_e32 v102, 63, v155
	v_lshlrev_b32_e32 v103, 4, v102
	s_waitcnt lgkmcnt(0)
	s_add_i32 s46, s41, 0x0
	s_cmp_lt_u32 s46, 0x80
	s_cbranch_scc0 .Lmy_tf0_s1
	s_lshr_b32 s16, s46, 3
	s_and_b32 s18, s46, 7
	s_mul_i32 s20, s32, 0x900000
	s_add_u32 s0, s60, s20
	s_addc_u32 s1, s61, 0
	s_add_u32 s0, s0, 0x400
	s_addc_u32 s1, s1, 0
	s_mul_i32 s20, s32, 0x500000
	s_add_u32 s20, s20, 0x500000
	s_movk_i32 s4, 0x2400
	s_movk_i32 s6, 0x800
	s_mov_b32 s50, 13
	s_branch .Lmy_tf0_sd
.Lmy_tf0_s1:
	s_cmp_lt_u32 s46, 0xc0
	s_cbranch_scc0 .Lmy_tf0_s2
	s_sub_i32 s46, s46, 0x80
	s_lshr_b32 s16, s46, 2
	s_and_b32 s18, s46, 3
	s_lshl_b32 s20, s32, 22
	s_add_u32 s0, s62, s20
	s_addc_u32 s1, s63, 0
	s_lshl_b32 s20, s32, 21
	s_add_u32 s20, s20, 0x1800000
	s_movk_i32 s4, 0x1000
	s_movk_i32 s6, 0x800
	s_mov_b32 s50, 13
	s_branch .Lmy_tf0_sd
.Lmy_tf0_s2:
	s_cmp_lt_u32 s46, 0x1c0
	s_cbranch_scc0 .Lmy_tf0_s3
	s_sub_i32 s46, s46, 0xc0
	s_lshr_b32 s16, s46, 4
	s_and_b32 s18, s46, 15
	s_lshl_b32 s20, s32, 24
	s_add_u32 s0, s64, s20
	s_addc_u32 s1, s65, 0
	s_lshl_b32 s20, s32, 23
	s_add_u32 s20, s20, 0x2000000
	s_movk_i32 s4, 0x4000
	s_movk_i32 s6, 0x800
	s_mov_b32 s50, 13
	s_branch .Lmy_tf0_sd
.Lmy_tf0_s3:
	s_sub_i32 s46, s46, 0x1c0
	s_lshr_b32 s16, s46, 2
	s_and_b32 s18, s46, 3
	s_lshl_b32 s20, s32, 24
	s_add_u32 s0, s68, s20
	s_addc_u32 s1, s69, 0
	s_lshl_b32 s20, s32, 23
	s_add_u32 s20, s20, 0x4000000
	s_movk_i32 s4, 0x1000
	s_movk_i32 s6, 0x2000
	s_mov_b32 s50, 15
.Lmy_tf0_sd:
	s_add_u32 s2, s88, s20
	s_addc_u32 s3, s89, 0
	s_lshl_b32 s48, s18, 8
	s_mul_i32 s48, s48, s6
	s_lshl_b32 s20, s16, 7
	s_add_u32 s48, s48, s20
	s_lshl_b32 s20, s44, 4
	s_add_u32 s48, s48, s20
	s_add_u32 s2, s2, s48
	s_addc_u32 s3, s3, 0
	s_lshl_b32 s20, s16, 6
	s_lshl_b32 s48, s44, 3
	s_add_u32 s20, s20, s48
	s_mul_i32 s20, s20, s4
	s_lshl_b32 s48, s18, 10
	s_add_u32 s20, s20, s48
	s_add_u32 s0, s0, s20
	s_addc_u32 s1, s1, 0
	v_lshlrev_b32_e32 v104, s50, v102
	global_load_dwordx4 v[118:121], v103, s[0:1] nt
	s_add_u32 s0, s0, s4
	s_addc_u32 s1, s1, 0
	global_load_dwordx4 v[122:125], v103, s[0:1] nt
	s_add_u32 s0, s0, s4
	s_addc_u32 s1, s1, 0
	global_load_dwordx4 v[126:129], v103, s[0:1] nt
	s_add_u32 s0, s0, s4
	s_addc_u32 s1, s1, 0
	global_load_dwordx4 v[130:133], v103, s[0:1] nt
	s_add_u32 s0, s0, s4
	s_addc_u32 s1, s1, 0
	global_load_dwordx4 v[134:137], v103, s[0:1] nt
	s_add_u32 s0, s0, s4
	s_addc_u32 s1, s1, 0
	global_load_dwordx4 v[138:141], v103, s[0:1] nt
	s_add_u32 s0, s0, s4
	s_addc_u32 s1, s1, 0
	global_load_dwordx4 v[142:145], v103, s[0:1] nt
	s_add_u32 s0, s0, s4
	s_addc_u32 s1, s1, 0
	global_load_dwordx4 v[146:149], v103, s[0:1] nt
	s_add_i32 s46, s41, 0xb0
	s_cmp_lt_u32 s46, 0x80
	s_cbranch_scc0 .Lmy_tf1_s1
	s_lshr_b32 s16, s46, 3
	s_and_b32 s18, s46, 7
	s_mul_i32 s20, s32, 0x900000
	s_add_u32 s0, s60, s20
	s_addc_u32 s1, s61, 0
	s_add_u32 s0, s0, 0x400
	s_addc_u32 s1, s1, 0
	s_mul_i32 s20, s32, 0x500000
	s_add_u32 s20, s20, 0x500000
	s_movk_i32 s4, 0x2400
	s_movk_i32 s9, 0x800
	s_mov_b32 s50, 13
	s_branch .Lmy_tf1_sd
.Lmy_tf1_s1:
	s_cmp_lt_u32 s46, 0xc0
	s_cbranch_scc0 .Lmy_tf1_s2
	s_sub_i32 s46, s46, 0x80
	s_lshr_b32 s16, s46, 2
	s_and_b32 s18, s46, 3
	s_lshl_b32 s20, s32, 22
	s_add_u32 s0, s62, s20
	s_addc_u32 s1, s63, 0
	s_lshl_b32 s20, s32, 21
	s_add_u32 s20, s20, 0x1800000
	s_movk_i32 s4, 0x1000
	s_movk_i32 s9, 0x800
	s_mov_b32 s50, 13
	s_branch .Lmy_tf1_sd
.Lmy_tf1_s2:
	s_cmp_lt_u32 s46, 0x1c0
	s_cbranch_scc0 .Lmy_tf1_s3
	s_sub_i32 s46, s46, 0xc0
	s_lshr_b32 s16, s46, 4
	s_and_b32 s18, s46, 15
	s_lshl_b32 s20, s32, 24
	s_add_u32 s0, s64, s20
	s_addc_u32 s1, s65, 0
	s_lshl_b32 s20, s32, 23
	s_add_u32 s20, s20, 0x2000000
	s_movk_i32 s4, 0x4000
	s_movk_i32 s9, 0x800
	s_mov_b32 s50, 13
	s_branch .Lmy_tf1_sd
.Lmy_tf1_s3:
	s_sub_i32 s46, s46, 0x1c0
	s_lshr_b32 s16, s46, 2
	s_and_b32 s18, s46, 3
	s_lshl_b32 s20, s32, 24
	s_add_u32 s0, s68, s20
	s_addc_u32 s1, s69, 0
	s_lshl_b32 s20, s32, 23
	s_add_u32 s20, s20, 0x4000000
	s_movk_i32 s4, 0x1000
	s_movk_i32 s9, 0x2000
	s_mov_b32 s50, 15
.Lmy_tf1_sd:
	s_add_u32 s10, s88, s20
	s_addc_u32 s11, s89, 0
	s_lshl_b32 s48, s18, 8
	s_mul_i32 s48, s48, s9
	s_lshl_b32 s20, s16, 7
	s_add_u32 s48, s48, s20
	s_lshl_b32 s20, s44, 4
	s_add_u32 s48, s48, s20
	s_add_u32 s10, s10, s48
	s_addc_u32 s11, s11, 0
	s_lshl_b32 s20, s16, 6
	s_lshl_b32 s48, s44, 3
	s_add_u32 s20, s20, s48
	s_mul_i32 s20, s20, s4
	s_lshl_b32 s48, s18, 10
	s_add_u32 s20, s20, s48
	s_add_u32 s0, s0, s20
	s_addc_u32 s1, s1, 0
	v_lshlrev_b32_e32 v105, s50, v102
	global_load_dwordx4 v[176:179], v103, s[0:1] nt
	s_add_u32 s0, s0, s4
	s_addc_u32 s1, s1, 0
	global_load_dwordx4 v[180:183], v103, s[0:1] nt
	s_add_u32 s0, s0, s4
	s_addc_u32 s1, s1, 0
	global_load_dwordx4 v[184:187], v103, s[0:1] nt
	s_add_u32 s0, s0, s4
	s_addc_u32 s1, s1, 0
	global_load_dwordx4 v[188:191], v103, s[0:1] nt
	s_add_u32 s0, s0, s4
	s_addc_u32 s1, s1, 0
	global_load_dwordx4 v[192:195], v103, s[0:1] nt
	s_add_u32 s0, s0, s4
	s_addc_u32 s1, s1, 0
	global_load_dwordx4 v[196:199], v103, s[0:1] nt
	s_add_u32 s0, s0, s4
	s_addc_u32 s1, s1, 0
	global_load_dwordx4 v[200:203], v103, s[0:1] nt
	s_add_u32 s0, s0, s4
	s_addc_u32 s1, s1, 0
	global_load_dwordx4 v[204:207], v103, s[0:1] nt
	s_waitcnt vmcnt(8)
	v_cvt_pk_bf16_f32 v80, v118, v122
	v_cvt_pk_bf16_f32 v81, v126, v130
	v_cvt_pk_bf16_f32 v82, v134, v138
	v_cvt_pk_bf16_f32 v83, v142, v146
	v_cvt_pk_bf16_f32 v84, v119, v123
	v_cvt_pk_bf16_f32 v85, v127, v131
	v_cvt_pk_bf16_f32 v86, v135, v139
	v_cvt_pk_bf16_f32 v87, v143, v147
	v_cvt_pk_bf16_f32 v88, v120, v124
	v_cvt_pk_bf16_f32 v89, v128, v132
	v_cvt_pk_bf16_f32 v90, v136, v140
	v_cvt_pk_bf16_f32 v91, v144, v148
	v_cvt_pk_bf16_f32 v92, v121, v125
	v_cvt_pk_bf16_f32 v93, v129, v133
	v_cvt_pk_bf16_f32 v94, v137, v141
	v_cvt_pk_bf16_f32 v95, v145, v149
	global_store_dwordx4 v104, v[80:83], s[2:3]
	s_add_u32 s2, s2, s6
	s_addc_u32 s3, s3, 0
	global_store_dwordx4 v104, v[84:87], s[2:3]
	s_add_u32 s2, s2, s6
	s_addc_u32 s3, s3, 0
	global_store_dwordx4 v104, v[88:91], s[2:3]
	s_add_u32 s2, s2, s6
	s_addc_u32 s3, s3, 0
	global_store_dwordx4 v104, v[92:95], s[2:3]
	s_add_i32 s46, s41, 0x160
	s_cmp_lt_u32 s46, 0x80
	s_cbranch_scc0 .Lmy_tf2_s1
	s_lshr_b32 s16, s46, 3
	s_and_b32 s18, s46, 7
	s_mul_i32 s20, s32, 0x900000
	s_add_u32 s0, s60, s20
	s_addc_u32 s1, s61, 0
	s_add_u32 s0, s0, 0x400
	s_addc_u32 s1, s1, 0
	s_mul_i32 s20, s32, 0x500000
	s_add_u32 s20, s20, 0x500000
	s_movk_i32 s4, 0x2400
	s_movk_i32 s6, 0x800
	s_mov_b32 s50, 13
	s_branch .Lmy_tf2_sd

.Lmy_tf2_sd:
	s_add_u32 s2, s88, s20
	s_addc_u32 s3, s89, 0
	s_lshl_b32 s48, s18, 8
	s_mul_i32 s48, s48, s6
	s_lshl_b32 s20, s16, 7
	s_add_u32 s48, s48, s20
	s_lshl_b32 s20, s44, 4
	s_add_u32 s48, s48, s20
	s_add_u32 s2, s2, s48
	s_addc_u32 s3, s3, 0
	s_lshl_b32 s20, s16, 6
	s_lshl_b32 s48, s44, 3
	s_add_u32 s20, s20, s48
	s_mul_i32 s20, s20, s4
	s_lshl_b32 s48, s18, 10
	s_add_u32 s20, s20, s48
	s_add_u32 s0, s0, s20
	s_addc_u32 s1, s1, 0
	v_lshlrev_b32_e32 v104, s50, v102
	global_load_dwordx4 v[118:121], v103, s[0:1] nt
	s_add_u32 s0, s0, s4
	s_addc_u32 s1, s1, 0
	global_load_dwordx4 v[122:125], v103, s[0:1] nt
	s_add_u32 s0, s0, s4
	s_addc_u32 s1, s1, 0
	global_load_dwordx4 v[126:129], v103, s[0:1] nt
	s_add_u32 s0, s0, s4
	s_addc_u32 s1, s1, 0
	global_load_dwordx4 v[130:133], v103, s[0:1] nt
	s_add_u32 s0, s0, s4
	s_addc_u32 s1, s1, 0
	global_load_dwordx4 v[134:137], v103, s[0:1] nt
	s_add_u32 s0, s0, s4
	s_addc_u32 s1, s1, 0
	global_load_dwordx4 v[138:141], v103, s[0:1] nt
	s_add_u32 s0, s0, s4
	s_addc_u32 s1, s1, 0
	global_load_dwordx4 v[142:145], v103, s[0:1] nt
	s_add_u32 s0, s0, s4
	s_addc_u32 s1, s1, 0
	global_load_dwordx4 v[146:149], v103, s[0:1] nt
	s_waitcnt vmcnt(12)
	v_cvt_pk_bf16_f32 v234, v176, v180
	v_cvt_pk_bf16_f32 v235, v184, v188
	v_cvt_pk_bf16_f32 v236, v192, v196
	v_cvt_pk_bf16_f32 v237, v200, v204
	v_cvt_pk_bf16_f32 v238, v177, v181
	v_cvt_pk_bf16_f32 v239, v185, v189
	v_cvt_pk_bf16_f32 v240, v193, v197
	v_cvt_pk_bf16_f32 v241, v201, v205
	v_cvt_pk_bf16_f32 v242, v178, v182
	v_cvt_pk_bf16_f32 v243, v186, v190
	v_cvt_pk_bf16_f32 v244, v194, v198
	v_cvt_pk_bf16_f32 v245, v202, v206
	v_cvt_pk_bf16_f32 v246, v179, v183
	v_cvt_pk_bf16_f32 v247, v187, v191
	v_cvt_pk_bf16_f32 v248, v195, v199
	v_cvt_pk_bf16_f32 v249, v203, v207
	global_store_dwordx4 v105, v[234:237], s[10:11]
	s_add_u32 s10, s10, s9
	s_addc_u32 s11, s11, 0
	global_store_dwordx4 v105, v[238:241], s[10:11]
	s_add_u32 s10, s10, s9
	s_addc_u32 s11, s11, 0
	global_store_dwordx4 v105, v[242:245], s[10:11]
	s_add_u32 s10, s10, s9
	s_addc_u32 s11, s11, 0
	global_store_dwordx4 v105, v[246:249], s[10:11]
	s_add_i32 s46, s41, 0x210
	s_cmp_lt_u32 s46, 0x80
	s_cbranch_scc0 .Lmy_tf3_s1
	s_lshr_b32 s16, s46, 3
	s_and_b32 s18, s46, 7
	s_mul_i32 s20, s32, 0x900000
	s_add_u32 s0, s60, s20
	s_addc_u32 s1, s61, 0
	s_add_u32 s0, s0, 0x400
	s_addc_u32 s1, s1, 0
	s_mul_i32 s20, s32, 0x500000
	s_add_u32 s20, s20, 0x500000
	s_movk_i32 s4, 0x2400
	s_movk_i32 s9, 0x800
	s_mov_b32 s50, 13
	s_branch .Lmy_tf3_sd

.Lmy_tf3_sd:
	s_add_u32 s10, s88, s20
	s_addc_u32 s11, s89, 0
	s_lshl_b32 s48, s18, 8
	s_mul_i32 s48, s48, s9
	s_lshl_b32 s20, s16, 7
	s_add_u32 s48, s48, s20
	s_lshl_b32 s20, s44, 4
	s_add_u32 s48, s48, s20
	s_add_u32 s10, s10, s48
	s_addc_u32 s11, s11, 0
	s_lshl_b32 s20, s16, 6
	s_lshl_b32 s48, s44, 3
	s_add_u32 s20, s20, s48
	s_mul_i32 s20, s20, s4
	s_lshl_b32 s48, s18, 10
	s_add_u32 s20, s20, s48
	s_add_u32 s0, s0, s20
	s_addc_u32 s1, s1, 0
	v_lshlrev_b32_e32 v105, s50, v102
	global_load_dwordx4 v[176:179], v103, s[0:1] nt
	s_add_u32 s0, s0, s4
	s_addc_u32 s1, s1, 0
	global_load_dwordx4 v[180:183], v103, s[0:1] nt
	s_add_u32 s0, s0, s4
	s_addc_u32 s1, s1, 0
	global_load_dwordx4 v[184:187], v103, s[0:1] nt
	s_add_u32 s0, s0, s4
	s_addc_u32 s1, s1, 0
	global_load_dwordx4 v[188:191], v103, s[0:1] nt
	s_add_u32 s0, s0, s4
	s_addc_u32 s1, s1, 0
	global_load_dwordx4 v[192:195], v103, s[0:1] nt
	s_add_u32 s0, s0, s4
	s_addc_u32 s1, s1, 0
	global_load_dwordx4 v[196:199], v103, s[0:1] nt
	s_add_u32 s0, s0, s4
	s_addc_u32 s1, s1, 0
	global_load_dwordx4 v[200:203], v103, s[0:1] nt
	s_add_u32 s0, s0, s4
	s_addc_u32 s1, s1, 0
	global_load_dwordx4 v[204:207], v103, s[0:1] nt
	s_waitcnt vmcnt(12)
	v_cvt_pk_bf16_f32 v80, v118, v122
	v_cvt_pk_bf16_f32 v81, v126, v130
	v_cvt_pk_bf16_f32 v82, v134, v138
	v_cvt_pk_bf16_f32 v83, v142, v146
	v_cvt_pk_bf16_f32 v84, v119, v123
	v_cvt_pk_bf16_f32 v85, v127, v131
	v_cvt_pk_bf16_f32 v86, v135, v139
	v_cvt_pk_bf16_f32 v87, v143, v147
	v_cvt_pk_bf16_f32 v88, v120, v124
	v_cvt_pk_bf16_f32 v89, v128, v132
	v_cvt_pk_bf16_f32 v90, v136, v140
	v_cvt_pk_bf16_f32 v91, v144, v148
	v_cvt_pk_bf16_f32 v92, v121, v125
	v_cvt_pk_bf16_f32 v93, v129, v133
	v_cvt_pk_bf16_f32 v94, v137, v141
	v_cvt_pk_bf16_f32 v95, v145, v149
	global_store_dwordx4 v104, v[80:83], s[2:3]
	s_add_u32 s2, s2, s6
	s_addc_u32 s3, s3, 0
	global_store_dwordx4 v104, v[84:87], s[2:3]
	s_add_u32 s2, s2, s6
	s_addc_u32 s3, s3, 0
	global_store_dwordx4 v104, v[88:91], s[2:3]
	s_add_u32 s2, s2, s6
	s_addc_u32 s3, s3, 0
	global_store_dwordx4 v104, v[92:95], s[2:3]
	s_waitcnt vmcnt(4)
	v_cvt_pk_bf16_f32 v234, v176, v180
	v_cvt_pk_bf16_f32 v235, v184, v188
	v_cvt_pk_bf16_f32 v236, v192, v196
	v_cvt_pk_bf16_f32 v237, v200, v204
	v_cvt_pk_bf16_f32 v238, v177, v181
	v_cvt_pk_bf16_f32 v239, v185, v189
	v_cvt_pk_bf16_f32 v240, v193, v197
	v_cvt_pk_bf16_f32 v241, v201, v205
	v_cvt_pk_bf16_f32 v242, v178, v182
	v_cvt_pk_bf16_f32 v243, v186, v190
	v_cvt_pk_bf16_f32 v244, v194, v198
	v_cvt_pk_bf16_f32 v245, v202, v206
	v_cvt_pk_bf16_f32 v246, v179, v183
	v_cvt_pk_bf16_f32 v247, v187, v191
	v_cvt_pk_bf16_f32 v248, v195, v199
	v_cvt_pk_bf16_f32 v249, v203, v207
	global_store_dwordx4 v105, v[234:237], s[10:11]
	s_add_u32 s10, s10, s9
	s_addc_u32 s11, s11, 0
	global_store_dwordx4 v105, v[238:241], s[10:11]
	s_add_u32 s10, s10, s9
	s_addc_u32 s11, s11, 0
	global_store_dwordx4 v105, v[242:245], s[10:11]
	s_add_u32 s10, s10, s9
	s_addc_u32 s11, s11, 0
	global_store_dwordx4 v105, v[246:249], s[10:11]
	s_mov_b64 exec, s[38:39]
	s_nop 0
	s_nop 0
	s_nop 0
	s_nop 0
	s_nop 0
	s_nop 0
	s_nop 0
	s_nop 0
	s_nop 0
	s_nop 0
	s_nop 0

.LBB0_86:
	s_andn2_b64 vcc, exec, s[2:3]
	v_writelane_b32 v254, s12, 54
	s_cbranch_vccnz .LBB0_570
	s_add_i32 s0, s12, -1
	s_mul_hi_i32 s1, s0, 0x92492493
	s_add_i32 s1, s1, s0
	s_lshr_b32 s2, s1, 31
	s_ashr_i32 s1, s1, 2
	s_add_i32 s2, s1, s2
	s_mul_i32 s1, s2, 7
	s_sub_i32 s47, s0, s1
	s_sub_i32 s0, s12, 22
	s_cmp_lt_u32 s0, 7
	s_cselect_b64 s[38:39], -1, 0
	s_cmp_gt_u32 s0, 6
	s_cselect_b64 s[0:1], -1, 0
	v_writelane_b32 v254, s0, 55
	s_mov_b64 s[50:51], 0
	s_nop 0
	v_writelane_b32 v254, s1, 56
	s_add_i32 s0, s12, 5
	v_readlane_b32 s56, v254, 4
	s_cmp_lt_u32 s0, 13
	v_readlane_b32 s70, v254, 18
	v_readlane_b32 s71, v254, 19
	s_cselect_b32 s48, s73, s71
	s_cselect_b32 s49, s72, s70
	s_ashr_i32 s3, s2, 31
	v_readlane_b32 s57, v254, 5
	v_readlane_b32 s58, v254, 6
	v_readlane_b32 s59, v254, 7
	v_readlane_b32 s60, v254, 8
	v_readlane_b32 s61, v254, 9
	v_readlane_b32 s62, v254, 10
	v_readlane_b32 s63, v254, 11
	v_readlane_b32 s64, v254, 12
	v_readlane_b32 s65, v254, 13
	v_readlane_b32 s66, v254, 14
	v_readlane_b32 s67, v254, 15
	v_readlane_b32 s68, v254, 16
	v_readlane_b32 s69, v254, 17
	s_mul_hi_i32 s0, s2, 0x36000
	v_writelane_b32 v254, s2, 57
	s_mul_i32 s1, s2, 0x36000
	s_mov_b64 s[58:59], 0
	v_writelane_b32 v254, s3, 58
	v_readlane_b32 s2, v251, 3
	v_readlane_b32 s3, v251, 4
	s_add_u32 s44, s2, s1
	s_addc_u32 s45, s3, s0
	v_writelane_b32 v254, s44, 59
	s_mov_b64 s[0:1], -1
	s_cmp_lt_i32 s47, 1
	v_writelane_b32 v254, s45, 60
	v_writelane_b32 v254, s47, 61
	s_cbranch_scc1 .LBB0_414
	s_cmp_gt_i32 s47, 1
	s_cbranch_scc0 .LBB0_263
	s_cmp_eq_u32 s47, 2
	s_mov_b64 s[58:59], -1
	s_cbranch_scc0 .LBB0_262
	s_and_b64 s[0:1], s[38:39], exec
	s_movk_i32 s0, 0x600
	s_cselect_b32 s37, s0, 0x610
	s_movk_i32 s0, 0x618
	s_cselect_b32 s41, 0x600, s0
	s_movk_i32 s0, 0x638
	s_cselect_b32 s92, 0x600, s0
	s_movk_i32 s0, 0x658
	s_cselect_b32 s93, 0x600, s0
	s_movk_i32 s0, 0x658
	v_readlane_b32 s18, v254, 57
	s_cselect_b32 s94, 0x600, s0
	s_lshl_b32 s0, s18, 6
	s_ashr_i32 s1, s0, 31
	s_lshl_b64 s[0:1], s[0:1], 2
	s_add_u32 s22, s88, s0
	s_addc_u32 s23, s89, s1
	s_lshl_b32 s16, s18, 9
	v_readlane_b32 s19, v254, 58
	s_add_i32 s2, s18, 1
	v_writelane_b32 v254, s16, 62
	s_ashr_i32 s3, s2, 31
	s_waitcnt lgkmcnt(0)
	s_lshl_b32 s8, s18, 1
	s_lshl_b32 s10, s18, 8
	v_readlane_b32 s72, v254, 4
	s_lshl_b64 s[4:5], s[2:3], 24
	s_lshl_b64 s[6:7], s[2:3], 23
	s_lshl_b32 s95, s18, 2
	s_ashr_i32 s9, s8, 31
	s_ashr_i32 s11, s10, 31
	v_readlane_b32 s82, v254, 14
	v_readlane_b32 s83, v254, 15
	s_add_u32 s16, s82, s4
	s_addc_u32 s17, s83, s5
	v_readlane_b32 s73, v254, 5
	v_readlane_b32 s74, v254, 6
	v_readlane_b32 s75, v254, 7
	v_readlane_b32 s76, v254, 8
	v_readlane_b32 s77, v254, 9
	v_readlane_b32 s78, v254, 10
	v_readlane_b32 s79, v254, 11
	v_readlane_b32 s80, v254, 12
	v_readlane_b32 s81, v254, 13
	v_readlane_b32 s84, v254, 16
	v_readlane_b32 s85, v254, 17
	v_readlane_b32 s86, v254, 18
	v_readlane_b32 s87, v254, 19
	v_writelane_b32 v254, s16, 63
	v_readlane_b32 s56, v252, 35
	v_readlane_b32 s58, v252, 37
	v_writelane_b32 v255, s17, 0
	v_readlane_b32 s16, v252, 55
	s_add_u32 s24, s16, s6
	v_readlane_b32 s16, v252, 56
	s_addc_u32 s25, s16, s7
	v_writelane_b32 v255, s24, 1
	s_add_u32 s4, s80, s4
	s_addc_u32 s5, s81, s5
	v_writelane_b32 v255, s25, 2
	v_writelane_b32 v255, s4, 3
	v_readlane_b32 s59, v252, 38
	s_mul_hi_i32 s12, s2, 0x900000
	v_writelane_b32 v255, s5, 4
	v_readlane_b32 s4, v252, 57
	s_add_u32 s6, s4, s6
	v_readlane_b32 s4, v252, 58
	s_addc_u32 s7, s4, s7
	s_lshl_b64 s[4:5], s[2:3], 22
	v_writelane_b32 v255, s6, 5
	s_add_u32 s4, s58, s4
	s_addc_u32 s5, s59, s5
	v_writelane_b32 v255, s7, 6
	v_writelane_b32 v255, s4, 7
	s_mul_i32 s13, s2, 0x900000
	s_mul_hi_i32 s14, s2, 0x500000
	s_mul_i32 s15, s2, 0x500000
	v_writelane_b32 v255, s5, 8
	s_lshl_b64 s[2:3], s[2:3], 21
	v_readlane_b32 s4, v252, 59
	s_add_u32 s4, s4, s2
	v_readlane_b32 s2, v252, 60
	s_addc_u32 s5, s2, s3
	v_readlane_b32 s57, v252, 36
	s_add_u32 s2, s56, s13
	s_addc_u32 s3, s57, s12
	v_writelane_b32 v255, s4, 9
	s_add_u32 s2, s2, 0x400
	s_addc_u32 s3, s3, 0
	v_writelane_b32 v255, s5, 10
	v_writelane_b32 v255, s2, 11
	v_readlane_b32 s4, v252, 20
	v_readlane_b32 s5, v252, 21
	v_writelane_b32 v255, s3, 12
	s_add_u32 s2, s88, s15
	s_addc_u32 s3, s89, s14
	s_add_u32 s2, s2, 0x500000
	s_addc_u32 s3, s3, 0
	v_writelane_b32 v255, s2, 13
	v_readlane_b32 s70, v252, 49
	v_readlane_b32 s71, v252, 50
	v_writelane_b32 v255, s3, 14
	s_lshl_b64 s[2:3], s[8:9], 2
	s_add_u32 s2, s4, s2
	s_addc_u32 s3, s5, s3
	s_add_u32 s0, s78, s0
	s_addc_u32 s1, s79, s1
	v_readlane_b32 s62, v252, 41
	v_readlane_b32 s66, v252, 45
	v_readlane_b32 s67, v252, 46
	s_mov_b64 s[70:71], s[0:1]
	s_lshl_b64 s[0:1], s[10:11], 2
	v_readlane_b32 s63, v252, 42
	s_mov_b64 s[66:67], s[2:3]
	s_add_u32 s2, s62, s0
	v_readlane_b32 s64, v252, 43
	s_addc_u32 s3, s63, s1
	v_readlane_b32 s65, v252, 44
	v_writelane_b32 v255, s2, 15
	s_add_u32 s0, s64, s0
	s_addc_u32 s1, s65, s1
	v_writelane_b32 v255, s3, 16
	v_writelane_b32 v255, s0, 17
	v_readlane_b32 s60, v252, 39
	v_readlane_b32 s61, v252, 40
	v_writelane_b32 v255, s1, 18
	s_mul_i32 s0, s18, 0x744
	v_readlane_b32 s68, v252, 47
	v_readlane_b32 s69, v252, 48
	s_mov_b32 s13, 0x800000
	s_mov_b64 s[64:65], s[22:23]
	v_writelane_b32 v255, s0, 19
	s_mov_b64 s[10:11], 0x8000
	v_readfirstlane_b32 s98, v155
	s_lshr_b32 s98, s98, 6
	s_cmp_lg_u32 s98, 0
	s_cbranch_scc1 .Ldq_noprime
	s_mov_b64 s[0:1], exec
	s_mov_b32 s2, 0
	s_mov_b32 s3, 1
	s_mov_b64 exec, s[2:3]
	global_atomic_add v255, v1, v157, s[64:65] sc0
	s_mov_b64 exec, s[0:1]
